# gates-GEMM epilogue: gate_b loaded once per tile (was reloaded+waited 32x), packed f32 add/mul; on top of merge epilogue pipelining
# speedup vs baseline: 1.0342x; 1.0065x over previous
; __device__ __forceinline__ float fast_exp2(float x) { return __builtin_amdgcn_exp2f(x); }
; __device__ __forceinline__ float fast_rcp(float x) { return __builtin_amdgcn_rcpf(x); }
; #define EPI_LOOP_END } if (m == 3) asm volatile("" ::: "memory"); }
; __device__ __forceinline__ u32x4 pack8(f32x4 v0, f32x4 v1) { u32x4 w; w.x = cvt_pk_bf16(v0[0], v0[1]); w.y = cvt_pk_bf16(v0[2], v0[3]); w.z = cvt_pk_bf16(v1[0], v1[1]); w.w = cvt_pk_bf16(v1[2], v1[3]); return w; }
; __device__ __forceinline__ float sigmoidf_(float x) { return fast_rcp(1.0f + fast_exp2(-x * LOG2E)); }
;     __device__ __forceinline__ void operator()(f32x4 (&acc)[2][2][4][2], const Unit& u, int wr, int wc, int fr, int fq) const {
;         const int b = u.pn >> 2; const size_t cbase = (size_t)b * (b == 1 ? O_DK : O_FK / 2);     const int wave = wr * 4 + wc, lane = fq * 16 + fr;
;         EPI_LOOP_BEGIN
;             (void)row;
;             const f32x4 b0 = *(const f32x4*)(gb + col), b1 = *(const f32x4*)(gb + col + 4);
; #pragma unroll
;             for (int e = 0; e < 4; ++e) { v0[e] = sigmoidf_(v0[e] + b0[e]); v1[e] = sigmoidf_(v1[e] + b1[e]); }
;             *(u32x4*)(O + gate_frag_off(u.pm, u.pn & 3, wave, ai, m, bj, lane, cbase)) = pack8(v0, v1);
;         EPI_LOOP_END
.LBB0_834:
	v_lshl_or_b32 v144, s3, 8, v146
	v_ashrrev_i32_e32 v145, 31, v144
	v_lshl_add_u64 v[144:145], v[144:145], 2, s[8:9]
	global_load_dwordx4 v[148:151], v[144:145], off
	global_load_dwordx4 v[152:155], v[144:145], off offset:16
	global_load_dwordx4 v[156:159], v[144:145], off offset:512
	global_load_dwordx4 v[160:163], v[144:145], off offset:528
	s_ashr_i32 s13, s3, 2
	s_cmp_eq_u32 s13, 1
	s_mov_b32 s15, 0x5000000
	s_cselect_b32 s15, s15, 0x4000000
	s_lshl_b32 s3, s3, 3
	s_lshl_b32 s2, s2, 5
	s_and_b32 s3, s3, 24
	s_or_b32 s2, s3, s2
	s_or_b32 s2, s2, s40
	s_lshl_b32 s2, s2, 4
	s_add_i32 s2, s2, s41
	s_mul_hi_i32 s21, s15, s13
	s_mul_i32 s20, s15, s13
	s_ashr_i32 s3, s2, 31
	v_lshl_add_u64 v[182:183], s[20:21], 1, v[138:139]
	s_lshl_b64 s[20:21], s[2:3], 10
	v_lshl_add_u64 v[182:183], v[182:183], 0, s[20:21]
	s_mov_b64 s[20:21], 0x1000
	v_lshl_add_u64 v[184:185], v[182:183], 0, s[20:21]
	v_lshl_add_u64 v[186:187], v[184:185], 0, s[20:21]
	v_lshl_add_u64 v[188:189], v[186:187], 0, s[20:21]
	s_mov_b32 s20, 0xbfb8aa3b
	s_mov_b32 s2, 1.0
	s_waitcnt vmcnt(0)
	v_pk_add_f32 v[126:127], v[126:127], v[148:149]
	v_pk_add_f32 v[128:129], v[128:129], v[150:151]
	v_pk_add_f32 v[122:123], v[122:123], v[152:153]
	v_pk_add_f32 v[124:125], v[124:125], v[154:155]
	v_pk_mul_f32 v[126:127], v[126:127], s[20:21] op_sel_hi:[1,0]
	v_pk_mul_f32 v[128:129], v[128:129], s[20:21] op_sel_hi:[1,0]
	v_pk_mul_f32 v[122:123], v[122:123], s[20:21] op_sel_hi:[1,0]
	v_pk_mul_f32 v[124:125], v[124:125], s[20:21] op_sel_hi:[1,0]
	v_exp_f32_e32 v126, v126
	v_exp_f32_e32 v127, v127
	v_exp_f32_e32 v128, v128
	v_exp_f32_e32 v129, v129
	v_exp_f32_e32 v122, v122
	v_exp_f32_e32 v123, v123
	v_exp_f32_e32 v124, v124
	v_exp_f32_e32 v125, v125
	v_pk_add_f32 v[126:127], v[126:127], s[2:3] op_sel_hi:[1,0]
	v_pk_add_f32 v[128:129], v[128:129], s[2:3] op_sel_hi:[1,0]
	v_pk_add_f32 v[122:123], v[122:123], s[2:3] op_sel_hi:[1,0]
	v_pk_add_f32 v[124:125], v[124:125], s[2:3] op_sel_hi:[1,0]
	v_rcp_f32_e32 v126, v126
	v_rcp_f32_e32 v127, v127
	v_rcp_f32_e32 v128, v128
	v_rcp_f32_e32 v129, v129
	v_rcp_f32_e32 v122, v122
	v_rcp_f32_e32 v123, v123
	v_rcp_f32_e32 v124, v124
	v_rcp_f32_e32 v125, v125
	v_cvt_pk_bf16_f32 v164, v126, v127
	v_cvt_pk_bf16_f32 v165, v128, v129
	v_cvt_pk_bf16_f32 v166, v122, v123
	v_cvt_pk_bf16_f32 v167, v124, v125
	global_store_dwordx4 v[182:183], v[164:167], off
	v_pk_add_f32 v[118:119], v[118:119], v[156:157]
	v_pk_add_f32 v[120:121], v[120:121], v[158:159]
	v_pk_add_f32 v[114:115], v[114:115], v[160:161]
	v_pk_add_f32 v[116:117], v[116:117], v[162:163]
	v_pk_mul_f32 v[118:119], v[118:119], s[20:21] op_sel_hi:[1,0]
	v_pk_mul_f32 v[120:121], v[120:121], s[20:21] op_sel_hi:[1,0]
	v_pk_mul_f32 v[114:115], v[114:115], s[20:21] op_sel_hi:[1,0]
	v_pk_mul_f32 v[116:117], v[116:117], s[20:21] op_sel_hi:[1,0]
	v_exp_f32_e32 v118, v118
	v_exp_f32_e32 v119, v119
	v_exp_f32_e32 v120, v120
	v_exp_f32_e32 v121, v121
	v_exp_f32_e32 v114, v114
	v_exp_f32_e32 v115, v115
	v_exp_f32_e32 v116, v116
	v_exp_f32_e32 v117, v117
	v_pk_add_f32 v[118:119], v[118:119], s[2:3] op_sel_hi:[1,0]
	v_pk_add_f32 v[120:121], v[120:121], s[2:3] op_sel_hi:[1,0]
	v_pk_add_f32 v[114:115], v[114:115], s[2:3] op_sel_hi:[1,0]
	v_pk_add_f32 v[116:117], v[116:117], s[2:3] op_sel_hi:[1,0]
	v_rcp_f32_e32 v118, v118
	v_rcp_f32_e32 v119, v119
	v_rcp_f32_e32 v120, v120
	v_rcp_f32_e32 v121, v121
	v_rcp_f32_e32 v114, v114
	v_rcp_f32_e32 v115, v115
	v_rcp_f32_e32 v116, v116
	v_rcp_f32_e32 v117, v117
	v_cvt_pk_bf16_f32 v168, v118, v119
	v_cvt_pk_bf16_f32 v169, v120, v121
	v_cvt_pk_bf16_f32 v170, v114, v115
	v_cvt_pk_bf16_f32 v171, v116, v117
	global_store_dwordx4 v[182:183], v[168:171], off offset:1024
	v_pk_add_f32 v[110:111], v[110:111], v[148:149]
	v_pk_add_f32 v[112:113], v[112:113], v[150:151]
	v_pk_add_f32 v[106:107], v[106:107], v[152:153]
	v_pk_add_f32 v[108:109], v[108:109], v[154:155]
	v_pk_mul_f32 v[110:111], v[110:111], s[20:21] op_sel_hi:[1,0]
	v_pk_mul_f32 v[112:113], v[112:113], s[20:21] op_sel_hi:[1,0]
	v_pk_mul_f32 v[106:107], v[106:107], s[20:21] op_sel_hi:[1,0]
	v_pk_mul_f32 v[108:109], v[108:109], s[20:21] op_sel_hi:[1,0]
	v_exp_f32_e32 v110, v110
	v_exp_f32_e32 v111, v111
	v_exp_f32_e32 v112, v112
	v_exp_f32_e32 v113, v113
	v_exp_f32_e32 v106, v106
	v_exp_f32_e32 v107, v107
	v_exp_f32_e32 v108, v108
	v_exp_f32_e32 v109, v109
	v_pk_add_f32 v[110:111], v[110:111], s[2:3] op_sel_hi:[1,0]
	v_pk_add_f32 v[112:113], v[112:113], s[2:3] op_sel_hi:[1,0]
	v_pk_add_f32 v[106:107], v[106:107], s[2:3] op_sel_hi:[1,0]
	v_pk_add_f32 v[108:109], v[108:109], s[2:3] op_sel_hi:[1,0]
	v_rcp_f32_e32 v110, v110
	v_rcp_f32_e32 v111, v111
	v_rcp_f32_e32 v112, v112
	v_rcp_f32_e32 v113, v113
	v_rcp_f32_e32 v106, v106
	v_rcp_f32_e32 v107, v107
	v_rcp_f32_e32 v108, v108
	v_rcp_f32_e32 v109, v109
	v_cvt_pk_bf16_f32 v172, v110, v111
	v_cvt_pk_bf16_f32 v173, v112, v113
	v_cvt_pk_bf16_f32 v174, v106, v107
	v_cvt_pk_bf16_f32 v175, v108, v109
	global_store_dwordx4 v[182:183], v[172:175], off offset:2048
	v_pk_add_f32 v[102:103], v[102:103], v[156:157]
	v_pk_add_f32 v[104:105], v[104:105], v[158:159]
	v_pk_add_f32 v[98:99], v[98:99], v[160:161]
	v_pk_add_f32 v[100:101], v[100:101], v[162:163]
	v_pk_mul_f32 v[102:103], v[102:103], s[20:21] op_sel_hi:[1,0]
	v_pk_mul_f32 v[104:105], v[104:105], s[20:21] op_sel_hi:[1,0]
	v_pk_mul_f32 v[98:99], v[98:99], s[20:21] op_sel_hi:[1,0]
	v_pk_mul_f32 v[100:101], v[100:101], s[20:21] op_sel_hi:[1,0]
	v_exp_f32_e32 v102, v102
	v_exp_f32_e32 v103, v103
	v_exp_f32_e32 v104, v104
	v_exp_f32_e32 v105, v105
	v_exp_f32_e32 v98, v98
	v_exp_f32_e32 v99, v99
	v_exp_f32_e32 v100, v100
	v_exp_f32_e32 v101, v101
; __device__ __forceinline__ float sigmoidf_(float x) { return fast_rcp(1.0f + fast_exp2(-x * LOG2E)); }
; #define EPI_LOOP_END } if (m == 3) asm volatile("" ::: "memory"); }
; __device__ __forceinline__ u32x4 pack8(f32x4 v0, f32x4 v1) { u32x4 w; w.x = cvt_pk_bf16(v0[0], v0[1]); w.y = cvt_pk_bf16(v0[2], v0[3]); w.z = cvt_pk_bf16(v1[0], v1[1]); w.w = cvt_pk_bf16(v1[2], v1[3]); return w; }
;     __device__ __forceinline__ void operator()(f32x4 (&acc)[2][2][4][2], const Unit& u, int wr, int wc, int fr, int fq) const {
;     ...
;         EPI_LOOP_BEGIN
;             (void)row;
;             const f32x4 b0 = *(const f32x4*)(gb + col), b1 = *(const f32x4*)(gb + col + 4);
; #pragma unroll
;             for (int e = 0; e < 4; ++e) { v0[e] = sigmoidf_(v0[e] + b0[e]); v1[e] = sigmoidf_(v1[e] + b1[e]); }
;             *(u32x4*)(O + gate_frag_off(u.pm, u.pn & 3, wave, ai, m, bj, lane, cbase)) = pack8(v0, v1);
;         EPI_LOOP_END
	v_pk_add_f32 v[102:103], v[102:103], s[2:3] op_sel_hi:[1,0]
	v_pk_add_f32 v[104:105], v[104:105], s[2:3] op_sel_hi:[1,0]
	v_pk_add_f32 v[98:99], v[98:99], s[2:3] op_sel_hi:[1,0]
	v_pk_add_f32 v[100:101], v[100:101], s[2:3] op_sel_hi:[1,0]
	v_rcp_f32_e32 v102, v102
	v_rcp_f32_e32 v103, v103
	v_rcp_f32_e32 v104, v104
	v_rcp_f32_e32 v105, v105
	v_rcp_f32_e32 v98, v98
	v_rcp_f32_e32 v99, v99
	v_rcp_f32_e32 v100, v100
	v_rcp_f32_e32 v101, v101
	v_cvt_pk_bf16_f32 v176, v102, v103
	v_cvt_pk_bf16_f32 v177, v104, v105
	v_cvt_pk_bf16_f32 v178, v98, v99
	v_cvt_pk_bf16_f32 v179, v100, v101
	global_store_dwordx4 v[182:183], v[176:179], off offset:3072
	v_pk_add_f32 v[94:95], v[94:95], v[148:149]
	v_pk_add_f32 v[96:97], v[96:97], v[150:151]
	v_pk_add_f32 v[90:91], v[90:91], v[152:153]
	v_pk_add_f32 v[92:93], v[92:93], v[154:155]
	v_pk_mul_f32 v[94:95], v[94:95], s[20:21] op_sel_hi:[1,0]
	v_pk_mul_f32 v[96:97], v[96:97], s[20:21] op_sel_hi:[1,0]
	v_pk_mul_f32 v[90:91], v[90:91], s[20:21] op_sel_hi:[1,0]
	v_pk_mul_f32 v[92:93], v[92:93], s[20:21] op_sel_hi:[1,0]
	v_exp_f32_e32 v94, v94
	v_exp_f32_e32 v95, v95
	v_exp_f32_e32 v96, v96
	v_exp_f32_e32 v97, v97
	v_exp_f32_e32 v90, v90
	v_exp_f32_e32 v91, v91
	v_exp_f32_e32 v92, v92
	v_exp_f32_e32 v93, v93
	v_pk_add_f32 v[94:95], v[94:95], s[2:3] op_sel_hi:[1,0]
	v_pk_add_f32 v[96:97], v[96:97], s[2:3] op_sel_hi:[1,0]
	v_pk_add_f32 v[90:91], v[90:91], s[2:3] op_sel_hi:[1,0]
	v_pk_add_f32 v[92:93], v[92:93], s[2:3] op_sel_hi:[1,0]
	v_rcp_f32_e32 v94, v94
	v_rcp_f32_e32 v95, v95
	v_rcp_f32_e32 v96, v96
	v_rcp_f32_e32 v97, v97
	v_rcp_f32_e32 v90, v90
	v_rcp_f32_e32 v91, v91
	v_rcp_f32_e32 v92, v92
	v_rcp_f32_e32 v93, v93
	v_cvt_pk_bf16_f32 v164, v94, v95
	v_cvt_pk_bf16_f32 v165, v96, v97
	v_cvt_pk_bf16_f32 v166, v90, v91
	v_cvt_pk_bf16_f32 v167, v92, v93
	global_store_dwordx4 v[184:185], v[164:167], off
	v_pk_add_f32 v[86:87], v[86:87], v[156:157]
	v_pk_add_f32 v[88:89], v[88:89], v[158:159]
	v_pk_add_f32 v[82:83], v[82:83], v[160:161]
	v_pk_add_f32 v[84:85], v[84:85], v[162:163]
	v_pk_mul_f32 v[86:87], v[86:87], s[20:21] op_sel_hi:[1,0]
	v_pk_mul_f32 v[88:89], v[88:89], s[20:21] op_sel_hi:[1,0]
	v_pk_mul_f32 v[82:83], v[82:83], s[20:21] op_sel_hi:[1,0]
	v_pk_mul_f32 v[84:85], v[84:85], s[20:21] op_sel_hi:[1,0]
	v_exp_f32_e32 v86, v86
	v_exp_f32_e32 v87, v87
	v_exp_f32_e32 v88, v88
	v_exp_f32_e32 v89, v89
	v_exp_f32_e32 v82, v82
	v_exp_f32_e32 v83, v83
	v_exp_f32_e32 v84, v84
	v_exp_f32_e32 v85, v85
	v_pk_add_f32 v[86:87], v[86:87], s[2:3] op_sel_hi:[1,0]
	v_pk_add_f32 v[88:89], v[88:89], s[2:3] op_sel_hi:[1,0]
	v_pk_add_f32 v[82:83], v[82:83], s[2:3] op_sel_hi:[1,0]
	v_pk_add_f32 v[84:85], v[84:85], s[2:3] op_sel_hi:[1,0]
	v_rcp_f32_e32 v86, v86
	v_rcp_f32_e32 v87, v87
	v_rcp_f32_e32 v88, v88
	v_rcp_f32_e32 v89, v89
	v_rcp_f32_e32 v82, v82
	v_rcp_f32_e32 v83, v83
	v_rcp_f32_e32 v84, v84
	v_rcp_f32_e32 v85, v85
	v_cvt_pk_bf16_f32 v168, v86, v87
	v_cvt_pk_bf16_f32 v169, v88, v89
	v_cvt_pk_bf16_f32 v170, v82, v83
	v_cvt_pk_bf16_f32 v171, v84, v85
	global_store_dwordx4 v[184:185], v[168:171], off offset:1024
	v_pk_add_f32 v[78:79], v[78:79], v[148:149]
	v_pk_add_f32 v[80:81], v[80:81], v[150:151]
	v_pk_add_f32 v[74:75], v[74:75], v[152:153]
	v_pk_add_f32 v[76:77], v[76:77], v[154:155]
	v_pk_mul_f32 v[78:79], v[78:79], s[20:21] op_sel_hi:[1,0]
	v_pk_mul_f32 v[80:81], v[80:81], s[20:21] op_sel_hi:[1,0]
	v_pk_mul_f32 v[74:75], v[74:75], s[20:21] op_sel_hi:[1,0]
	v_pk_mul_f32 v[76:77], v[76:77], s[20:21] op_sel_hi:[1,0]
	v_exp_f32_e32 v78, v78
	v_exp_f32_e32 v79, v79
	v_exp_f32_e32 v80, v80
	v_exp_f32_e32 v81, v81
	v_exp_f32_e32 v74, v74
	v_exp_f32_e32 v75, v75
	v_exp_f32_e32 v76, v76
	v_exp_f32_e32 v77, v77
	v_pk_add_f32 v[78:79], v[78:79], s[2:3] op_sel_hi:[1,0]
	v_pk_add_f32 v[80:81], v[80:81], s[2:3] op_sel_hi:[1,0]
	v_pk_add_f32 v[74:75], v[74:75], s[2:3] op_sel_hi:[1,0]
	v_pk_add_f32 v[76:77], v[76:77], s[2:3] op_sel_hi:[1,0]
	v_rcp_f32_e32 v78, v78
	v_rcp_f32_e32 v79, v79
	v_rcp_f32_e32 v80, v80
	v_rcp_f32_e32 v81, v81
	v_rcp_f32_e32 v74, v74
	v_rcp_f32_e32 v75, v75
	v_rcp_f32_e32 v76, v76
	v_rcp_f32_e32 v77, v77
	v_cvt_pk_bf16_f32 v172, v78, v79
	v_cvt_pk_bf16_f32 v173, v80, v81
	v_cvt_pk_bf16_f32 v174, v74, v75
	v_cvt_pk_bf16_f32 v175, v76, v77
	global_store_dwordx4 v[184:185], v[172:175], off offset:2048
	v_pk_add_f32 v[70:71], v[70:71], v[156:157]
	v_pk_add_f32 v[72:73], v[72:73], v[158:159]
	v_pk_add_f32 v[66:67], v[66:67], v[160:161]
	v_pk_add_f32 v[68:69], v[68:69], v[162:163]
	v_pk_mul_f32 v[70:71], v[70:71], s[20:21] op_sel_hi:[1,0]
	v_pk_mul_f32 v[72:73], v[72:73], s[20:21] op_sel_hi:[1,0]
	v_pk_mul_f32 v[66:67], v[66:67], s[20:21] op_sel_hi:[1,0]
	v_pk_mul_f32 v[68:69], v[68:69], s[20:21] op_sel_hi:[1,0]
	v_exp_f32_e32 v70, v70
	v_exp_f32_e32 v71, v71
	v_exp_f32_e32 v72, v72
	v_exp_f32_e32 v73, v73
	v_exp_f32_e32 v66, v66
	v_exp_f32_e32 v67, v67
	v_exp_f32_e32 v68, v68
	v_exp_f32_e32 v69, v69
	v_pk_add_f32 v[70:71], v[70:71], s[2:3] op_sel_hi:[1,0]
	v_pk_add_f32 v[72:73], v[72:73], s[2:3] op_sel_hi:[1,0]
	v_pk_add_f32 v[66:67], v[66:67], s[2:3] op_sel_hi:[1,0]
	v_pk_add_f32 v[68:69], v[68:69], s[2:3] op_sel_hi:[1,0]
	v_rcp_f32_e32 v70, v70
	v_rcp_f32_e32 v71, v71
	v_rcp_f32_e32 v72, v72
	v_rcp_f32_e32 v73, v73
	v_rcp_f32_e32 v66, v66
	v_rcp_f32_e32 v67, v67
	v_rcp_f32_e32 v68, v68
	v_rcp_f32_e32 v69, v69
	v_cvt_pk_bf16_f32 v176, v70, v71
	v_cvt_pk_bf16_f32 v177, v72, v73
	v_cvt_pk_bf16_f32 v178, v66, v67
	v_cvt_pk_bf16_f32 v179, v68, v69
	global_store_dwordx4 v[184:185], v[176:179], off offset:3072
	v_pk_add_f32 v[62:63], v[62:63], v[148:149]
	v_pk_add_f32 v[64:65], v[64:65], v[150:151]
; __device__ __forceinline__ float sigmoidf_(float x) { return fast_rcp(1.0f + fast_exp2(-x * LOG2E)); }
; #define EPI_LOOP_END } if (m == 3) asm volatile("" ::: "memory"); }
; __device__ __forceinline__ u32x4 pack8(f32x4 v0, f32x4 v1) { u32x4 w; w.x = cvt_pk_bf16(v0[0], v0[1]); w.y = cvt_pk_bf16(v0[2], v0[3]); w.z = cvt_pk_bf16(v1[0], v1[1]); w.w = cvt_pk_bf16(v1[2], v1[3]); return w; }
;     __device__ __forceinline__ void operator()(f32x4 (&acc)[2][2][4][2], const Unit& u, int wr, int wc, int fr, int fq) const {
;     ...
;         EPI_LOOP_BEGIN
;             (void)row;
;             const f32x4 b0 = *(const f32x4*)(gb + col), b1 = *(const f32x4*)(gb + col + 4);
; #pragma unroll
;             for (int e = 0; e < 4; ++e) { v0[e] = sigmoidf_(v0[e] + b0[e]); v1[e] = sigmoidf_(v1[e] + b1[e]); }
;             *(u32x4*)(O + gate_frag_off(u.pm, u.pn & 3, wave, ai, m, bj, lane, cbase)) = pack8(v0, v1);
;         EPI_LOOP_END
	v_pk_add_f32 v[58:59], v[58:59], v[152:153]
	v_pk_add_f32 v[60:61], v[60:61], v[154:155]
	v_pk_mul_f32 v[62:63], v[62:63], s[20:21] op_sel_hi:[1,0]
	v_pk_mul_f32 v[64:65], v[64:65], s[20:21] op_sel_hi:[1,0]
	v_pk_mul_f32 v[58:59], v[58:59], s[20:21] op_sel_hi:[1,0]
	v_pk_mul_f32 v[60:61], v[60:61], s[20:21] op_sel_hi:[1,0]
	v_exp_f32_e32 v62, v62
	v_exp_f32_e32 v63, v63
	v_exp_f32_e32 v64, v64
	v_exp_f32_e32 v65, v65
	v_exp_f32_e32 v58, v58
	v_exp_f32_e32 v59, v59
	v_exp_f32_e32 v60, v60
	v_exp_f32_e32 v61, v61
	v_pk_add_f32 v[62:63], v[62:63], s[2:3] op_sel_hi:[1,0]
	v_pk_add_f32 v[64:65], v[64:65], s[2:3] op_sel_hi:[1,0]
	v_pk_add_f32 v[58:59], v[58:59], s[2:3] op_sel_hi:[1,0]
	v_pk_add_f32 v[60:61], v[60:61], s[2:3] op_sel_hi:[1,0]
	v_rcp_f32_e32 v62, v62
	v_rcp_f32_e32 v63, v63
	v_rcp_f32_e32 v64, v64
	v_rcp_f32_e32 v65, v65
	v_rcp_f32_e32 v58, v58
	v_rcp_f32_e32 v59, v59
	v_rcp_f32_e32 v60, v60
	v_rcp_f32_e32 v61, v61
	v_cvt_pk_bf16_f32 v164, v62, v63
	v_cvt_pk_bf16_f32 v165, v64, v65
	v_cvt_pk_bf16_f32 v166, v58, v59
	v_cvt_pk_bf16_f32 v167, v60, v61
	global_store_dwordx4 v[186:187], v[164:167], off
	v_pk_add_f32 v[54:55], v[54:55], v[156:157]
	v_pk_add_f32 v[56:57], v[56:57], v[158:159]
	v_pk_add_f32 v[50:51], v[50:51], v[160:161]
	v_pk_add_f32 v[52:53], v[52:53], v[162:163]
	v_pk_mul_f32 v[54:55], v[54:55], s[20:21] op_sel_hi:[1,0]
	v_pk_mul_f32 v[56:57], v[56:57], s[20:21] op_sel_hi:[1,0]
	v_pk_mul_f32 v[50:51], v[50:51], s[20:21] op_sel_hi:[1,0]
	v_pk_mul_f32 v[52:53], v[52:53], s[20:21] op_sel_hi:[1,0]
	v_exp_f32_e32 v54, v54
	v_exp_f32_e32 v55, v55
	v_exp_f32_e32 v56, v56
	v_exp_f32_e32 v57, v57
	v_exp_f32_e32 v50, v50
	v_exp_f32_e32 v51, v51
	v_exp_f32_e32 v52, v52
	v_exp_f32_e32 v53, v53
	v_pk_add_f32 v[54:55], v[54:55], s[2:3] op_sel_hi:[1,0]
	v_pk_add_f32 v[56:57], v[56:57], s[2:3] op_sel_hi:[1,0]
	v_pk_add_f32 v[50:51], v[50:51], s[2:3] op_sel_hi:[1,0]
	v_pk_add_f32 v[52:53], v[52:53], s[2:3] op_sel_hi:[1,0]
	v_rcp_f32_e32 v54, v54
	v_rcp_f32_e32 v55, v55
	v_rcp_f32_e32 v56, v56
	v_rcp_f32_e32 v57, v57
	v_rcp_f32_e32 v50, v50
	v_rcp_f32_e32 v51, v51
	v_rcp_f32_e32 v52, v52
	v_rcp_f32_e32 v53, v53
	v_cvt_pk_bf16_f32 v168, v54, v55
	v_cvt_pk_bf16_f32 v169, v56, v57
	v_cvt_pk_bf16_f32 v170, v50, v51
	v_cvt_pk_bf16_f32 v171, v52, v53
	global_store_dwordx4 v[186:187], v[168:171], off offset:1024
	v_pk_add_f32 v[46:47], v[46:47], v[148:149]
	v_pk_add_f32 v[48:49], v[48:49], v[150:151]
	v_pk_add_f32 v[42:43], v[42:43], v[152:153]
	v_pk_add_f32 v[44:45], v[44:45], v[154:155]
	v_pk_mul_f32 v[46:47], v[46:47], s[20:21] op_sel_hi:[1,0]
	v_pk_mul_f32 v[48:49], v[48:49], s[20:21] op_sel_hi:[1,0]
	v_pk_mul_f32 v[42:43], v[42:43], s[20:21] op_sel_hi:[1,0]
	v_pk_mul_f32 v[44:45], v[44:45], s[20:21] op_sel_hi:[1,0]
	v_exp_f32_e32 v46, v46
	v_exp_f32_e32 v47, v47
	v_exp_f32_e32 v48, v48
	v_exp_f32_e32 v49, v49
	v_exp_f32_e32 v42, v42
	v_exp_f32_e32 v43, v43
	v_exp_f32_e32 v44, v44
	v_exp_f32_e32 v45, v45
	v_pk_add_f32 v[46:47], v[46:47], s[2:3] op_sel_hi:[1,0]
	v_pk_add_f32 v[48:49], v[48:49], s[2:3] op_sel_hi:[1,0]
	v_pk_add_f32 v[42:43], v[42:43], s[2:3] op_sel_hi:[1,0]
	v_pk_add_f32 v[44:45], v[44:45], s[2:3] op_sel_hi:[1,0]
	v_rcp_f32_e32 v46, v46
	v_rcp_f32_e32 v47, v47
	v_rcp_f32_e32 v48, v48
	v_rcp_f32_e32 v49, v49
	v_rcp_f32_e32 v42, v42
	v_rcp_f32_e32 v43, v43
	v_rcp_f32_e32 v44, v44
	v_rcp_f32_e32 v45, v45
	v_cvt_pk_bf16_f32 v172, v46, v47
	v_cvt_pk_bf16_f32 v173, v48, v49
	v_cvt_pk_bf16_f32 v174, v42, v43
	v_cvt_pk_bf16_f32 v175, v44, v45
	global_store_dwordx4 v[186:187], v[172:175], off offset:2048
	v_pk_add_f32 v[38:39], v[38:39], v[156:157]
	v_pk_add_f32 v[40:41], v[40:41], v[158:159]
	v_pk_add_f32 v[34:35], v[34:35], v[160:161]
	v_pk_add_f32 v[36:37], v[36:37], v[162:163]
	v_pk_mul_f32 v[38:39], v[38:39], s[20:21] op_sel_hi:[1,0]
	v_pk_mul_f32 v[40:41], v[40:41], s[20:21] op_sel_hi:[1,0]
	v_pk_mul_f32 v[34:35], v[34:35], s[20:21] op_sel_hi:[1,0]
	v_pk_mul_f32 v[36:37], v[36:37], s[20:21] op_sel_hi:[1,0]
	v_exp_f32_e32 v38, v38
	v_exp_f32_e32 v39, v39
	v_exp_f32_e32 v40, v40
	v_exp_f32_e32 v41, v41
	v_exp_f32_e32 v34, v34
	v_exp_f32_e32 v35, v35
	v_exp_f32_e32 v36, v36
	v_exp_f32_e32 v37, v37
	v_pk_add_f32 v[38:39], v[38:39], s[2:3] op_sel_hi:[1,0]
	v_pk_add_f32 v[40:41], v[40:41], s[2:3] op_sel_hi:[1,0]
	v_pk_add_f32 v[34:35], v[34:35], s[2:3] op_sel_hi:[1,0]
	v_pk_add_f32 v[36:37], v[36:37], s[2:3] op_sel_hi:[1,0]
	v_rcp_f32_e32 v38, v38
	v_rcp_f32_e32 v39, v39
	v_rcp_f32_e32 v40, v40
	v_rcp_f32_e32 v41, v41
	v_rcp_f32_e32 v34, v34
	v_rcp_f32_e32 v35, v35
	v_rcp_f32_e32 v36, v36
	v_rcp_f32_e32 v37, v37
	v_cvt_pk_bf16_f32 v176, v38, v39
	v_cvt_pk_bf16_f32 v177, v40, v41
	v_cvt_pk_bf16_f32 v178, v34, v35
	v_cvt_pk_bf16_f32 v179, v36, v37
	global_store_dwordx4 v[186:187], v[176:179], off offset:3072
	v_pk_add_f32 v[30:31], v[30:31], v[148:149]
	v_pk_add_f32 v[32:33], v[32:33], v[150:151]
; __device__ __forceinline__ float sigmoidf_(float x) { return fast_rcp(1.0f + fast_exp2(-x * LOG2E)); }
; #define EPI_LOOP_END } if (m == 3) asm volatile("" ::: "memory"); }
; __device__ __forceinline__ u32x4 pack8(f32x4 v0, f32x4 v1) { u32x4 w; w.x = cvt_pk_bf16(v0[0], v0[1]); w.y = cvt_pk_bf16(v0[2], v0[3]); w.z = cvt_pk_bf16(v1[0], v1[1]); w.w = cvt_pk_bf16(v1[2], v1[3]); return w; }
;     __device__ __forceinline__ void operator()(f32x4 (&acc)[2][2][4][2], const Unit& u, int wr, int wc, int fr, int fq) const {
;     ...
;         EPI_LOOP_BEGIN
;             (void)row;
;             const f32x4 b0 = *(const f32x4*)(gb + col), b1 = *(const f32x4*)(gb + col + 4);
; #pragma unroll
;             for (int e = 0; e < 4; ++e) { v0[e] = sigmoidf_(v0[e] + b0[e]); v1[e] = sigmoidf_(v1[e] + b1[e]); }
;             *(u32x4*)(O + gate_frag_off(u.pm, u.pn & 3, wave, ai, m, bj, lane, cbase)) = pack8(v0, v1);
;         EPI_LOOP_END
	v_pk_add_f32 v[26:27], v[26:27], v[152:153]
	v_pk_add_f32 v[28:29], v[28:29], v[154:155]
	v_pk_mul_f32 v[30:31], v[30:31], s[20:21] op_sel_hi:[1,0]
	v_pk_mul_f32 v[32:33], v[32:33], s[20:21] op_sel_hi:[1,0]
	v_pk_mul_f32 v[26:27], v[26:27], s[20:21] op_sel_hi:[1,0]
	v_pk_mul_f32 v[28:29], v[28:29], s[20:21] op_sel_hi:[1,0]
	v_exp_f32_e32 v30, v30
	v_exp_f32_e32 v31, v31
	v_exp_f32_e32 v32, v32
	v_exp_f32_e32 v33, v33
	v_exp_f32_e32 v26, v26
	v_exp_f32_e32 v27, v27
	v_exp_f32_e32 v28, v28
	v_exp_f32_e32 v29, v29
	v_pk_add_f32 v[30:31], v[30:31], s[2:3] op_sel_hi:[1,0]
	v_pk_add_f32 v[32:33], v[32:33], s[2:3] op_sel_hi:[1,0]
	v_pk_add_f32 v[26:27], v[26:27], s[2:3] op_sel_hi:[1,0]
	v_pk_add_f32 v[28:29], v[28:29], s[2:3] op_sel_hi:[1,0]
	v_rcp_f32_e32 v30, v30
	v_rcp_f32_e32 v31, v31
	v_rcp_f32_e32 v32, v32
	v_rcp_f32_e32 v33, v33
	v_rcp_f32_e32 v26, v26
	v_rcp_f32_e32 v27, v27
	v_rcp_f32_e32 v28, v28
	v_rcp_f32_e32 v29, v29
	v_cvt_pk_bf16_f32 v164, v30, v31
	v_cvt_pk_bf16_f32 v165, v32, v33
	v_cvt_pk_bf16_f32 v166, v26, v27
	v_cvt_pk_bf16_f32 v167, v28, v29
	global_store_dwordx4 v[188:189], v[164:167], off
	v_pk_add_f32 v[22:23], v[22:23], v[156:157]
	v_pk_add_f32 v[24:25], v[24:25], v[158:159]
	v_pk_add_f32 v[18:19], v[18:19], v[160:161]
	v_pk_add_f32 v[20:21], v[20:21], v[162:163]
	v_pk_mul_f32 v[22:23], v[22:23], s[20:21] op_sel_hi:[1,0]
	v_pk_mul_f32 v[24:25], v[24:25], s[20:21] op_sel_hi:[1,0]
	v_pk_mul_f32 v[18:19], v[18:19], s[20:21] op_sel_hi:[1,0]
	v_pk_mul_f32 v[20:21], v[20:21], s[20:21] op_sel_hi:[1,0]
	v_exp_f32_e32 v22, v22
	v_exp_f32_e32 v23, v23
	v_exp_f32_e32 v24, v24
	v_exp_f32_e32 v25, v25
	v_exp_f32_e32 v18, v18
	v_exp_f32_e32 v19, v19
	v_exp_f32_e32 v20, v20
	v_exp_f32_e32 v21, v21
	v_pk_add_f32 v[22:23], v[22:23], s[2:3] op_sel_hi:[1,0]
	v_pk_add_f32 v[24:25], v[24:25], s[2:3] op_sel_hi:[1,0]
	v_pk_add_f32 v[18:19], v[18:19], s[2:3] op_sel_hi:[1,0]
	v_pk_add_f32 v[20:21], v[20:21], s[2:3] op_sel_hi:[1,0]
	v_rcp_f32_e32 v22, v22
	v_rcp_f32_e32 v23, v23
	v_rcp_f32_e32 v24, v24
	v_rcp_f32_e32 v25, v25
	v_rcp_f32_e32 v18, v18
	v_rcp_f32_e32 v19, v19
	v_rcp_f32_e32 v20, v20
	v_rcp_f32_e32 v21, v21
	v_cvt_pk_bf16_f32 v168, v22, v23
	v_cvt_pk_bf16_f32 v169, v24, v25
	v_cvt_pk_bf16_f32 v170, v18, v19
	v_cvt_pk_bf16_f32 v171, v20, v21
	global_store_dwordx4 v[188:189], v[168:171], off offset:1024
	v_pk_add_f32 v[14:15], v[14:15], v[148:149]
	v_pk_add_f32 v[16:17], v[16:17], v[150:151]
	v_pk_add_f32 v[10:11], v[10:11], v[152:153]
	v_pk_add_f32 v[12:13], v[12:13], v[154:155]
	v_pk_mul_f32 v[14:15], v[14:15], s[20:21] op_sel_hi:[1,0]
	v_pk_mul_f32 v[16:17], v[16:17], s[20:21] op_sel_hi:[1,0]
	v_pk_mul_f32 v[10:11], v[10:11], s[20:21] op_sel_hi:[1,0]
	v_pk_mul_f32 v[12:13], v[12:13], s[20:21] op_sel_hi:[1,0]
	v_exp_f32_e32 v14, v14
	v_exp_f32_e32 v15, v15
	v_exp_f32_e32 v16, v16
	v_exp_f32_e32 v17, v17
	v_exp_f32_e32 v10, v10
	v_exp_f32_e32 v11, v11
	v_exp_f32_e32 v12, v12
	v_exp_f32_e32 v13, v13
	v_pk_add_f32 v[14:15], v[14:15], s[2:3] op_sel_hi:[1,0]
	v_pk_add_f32 v[16:17], v[16:17], s[2:3] op_sel_hi:[1,0]
	v_pk_add_f32 v[10:11], v[10:11], s[2:3] op_sel_hi:[1,0]
	v_pk_add_f32 v[12:13], v[12:13], s[2:3] op_sel_hi:[1,0]
	v_rcp_f32_e32 v14, v14
	v_rcp_f32_e32 v15, v15
	v_rcp_f32_e32 v16, v16
	v_rcp_f32_e32 v17, v17
	v_rcp_f32_e32 v10, v10
	v_rcp_f32_e32 v11, v11
	v_rcp_f32_e32 v12, v12
	v_rcp_f32_e32 v13, v13
	v_cvt_pk_bf16_f32 v172, v14, v15
	v_cvt_pk_bf16_f32 v173, v16, v17
	v_cvt_pk_bf16_f32 v174, v10, v11
	v_cvt_pk_bf16_f32 v175, v12, v13
	global_store_dwordx4 v[188:189], v[172:175], off offset:2048
	v_pk_add_f32 v[6:7], v[6:7], v[156:157]
	v_pk_add_f32 v[8:9], v[8:9], v[158:159]
	v_pk_add_f32 v[2:3], v[2:3], v[160:161]
	v_pk_add_f32 v[4:5], v[4:5], v[162:163]
	v_pk_mul_f32 v[6:7], v[6:7], s[20:21] op_sel_hi:[1,0]
	v_pk_mul_f32 v[8:9], v[8:9], s[20:21] op_sel_hi:[1,0]
	v_pk_mul_f32 v[2:3], v[2:3], s[20:21] op_sel_hi:[1,0]
	v_pk_mul_f32 v[4:5], v[4:5], s[20:21] op_sel_hi:[1,0]
	v_exp_f32_e32 v6, v6
	v_exp_f32_e32 v7, v7
	v_exp_f32_e32 v8, v8
	v_exp_f32_e32 v9, v9
	v_exp_f32_e32 v2, v2
	v_exp_f32_e32 v3, v3
	v_exp_f32_e32 v4, v4
	v_exp_f32_e32 v5, v5
	v_pk_add_f32 v[6:7], v[6:7], s[2:3] op_sel_hi:[1,0]
	v_pk_add_f32 v[8:9], v[8:9], s[2:3] op_sel_hi:[1,0]
	v_pk_add_f32 v[2:3], v[2:3], s[2:3] op_sel_hi:[1,0]
	v_pk_add_f32 v[4:5], v[4:5], s[2:3] op_sel_hi:[1,0]
	v_rcp_f32_e32 v6, v6
	v_rcp_f32_e32 v7, v7
	v_rcp_f32_e32 v8, v8
	v_rcp_f32_e32 v9, v9
	v_rcp_f32_e32 v2, v2
	v_rcp_f32_e32 v3, v3
	v_rcp_f32_e32 v4, v4
	v_rcp_f32_e32 v5, v5
	v_cvt_pk_bf16_f32 v176, v6, v7
	v_cvt_pk_bf16_f32 v177, v8, v9
	v_cvt_pk_bf16_f32 v178, v2, v3
	v_cvt_pk_bf16_f32 v179, v4, v5
	global_store_dwordx4 v[188:189], v[176:179], off offset:3072
	s_andn2_b64 vcc, exec, s[6:7]
	s_mov_b64 s[2:3], -1
	s_cbranch_vccnz .LBB0_827
	s_andn2_b64 vcc, exec, s[4:5]
	s_cbranch_vccnz .LBB0_826
	s_barrier
	s_branch .LBB0_826
